# SwiGLU: align barrier moved below ssq-independent VALU, rs^2 folded into rcp via fma; unit headers: StaticOrder division by constant group size 8 replaced by shift/and
# speedup vs baseline: 1.0129x; 1.0011x over previous
.LBB0_149:
	s_add_i32 s61, s61, 1
	s_mul_i32 s4, s61, s64
	s_mul_hi_u32 s5, s61, s65
	s_add_i32 s5, s5, s4
	s_mul_i32 s4, s61, s65
	s_add_u32 s42, s4, s2
	s_addc_u32 s43, s5, s55
	v_cmp_gt_i64_e32 vcc, s[42:43], v[146:147]
	v_cmp_lt_i64_e64 s[4:5], s[42:43], v[144:145]
	s_cbranch_vccnz .LBB0_151
	s_ashr_i32 s24, s42, 31
	s_lshr_b32 s24, s24, 29
	s_add_i32 s24, s42, s24
	s_ashr_i32 s25, s24, 3
	s_and_b32 s24, s24, -8
	s_sub_i32 s24, s42, s24
	s_cmp_lt_i32 s24, 0
	s_cselect_b32 s26, s56, 0x160
	s_mul_i32 s24, s24, s26
	s_add_i32 s24, s24, s25
	s_mul_hi_i32 s25, s24, 0x2e8ba2e9
	s_lshr_b32 s26, s25, 31
	s_ashr_i32 s25, s25, 5
	s_add_i32 s25, s25, s26
	s_lshl_b32 s26, s25, 3
	s_mulk_i32 s25, 0xb0
	s_sub_i32 s25, s24, s25
	s_lshr_b32 s24, s25, 3
	s_and_b32 s25, s25, 7
	s_add_i32 s26, s26, s25

.Lz_post_p1:
	s_lshl_b32 s25, s46, 8
	v_add_u32_e32 v148, s25, v150
	v_ashrrev_i32_e32 v149, 31, v148
	v_lshl_add_u64 v[160:161], v[148:149], 2, s[8:9]
	global_load_dword v149, v[160:161], off
	global_load_dword v232, v[160:161], off offset:64
	global_load_dword v233, v[160:161], off offset:128
	global_load_dword v234, v[160:161], off offset:192
	global_load_dword v235, v[160:161], off offset:512
	global_load_dword v236, v[160:161], off offset:576
	global_load_dword v237, v[160:161], off offset:640
	global_load_dword v238, v[160:161], off offset:704
	v_pk_mul_f32 v[128:129], v[120:121], v[128:129]
	v_pk_mul_f32 v[126:127], v[118:119], v[126:127]
	v_pk_mul_f32 v[124:125], v[116:117], v[124:125]
	v_pk_mul_f32 v[160:161], v[114:115], v[122:123]
	v_add_u32_e32 v162, s25, v152
	s_lshl_b32 s46, s47, 7
	v_mov_b64_e32 v[122:123], s[12:13]
	s_ashr_i32 s47, s46, 31
	v_mad_i64_i32 v[164:165], s[48:49], v148, s68, v[122:123]
	s_lshl_b64 s[46:47], s[46:47], 1
	v_lshl_add_u64 v[164:165], v[164:165], 0, s[46:47]
	v_lshl_add_u64 v[164:165], v[164:165], 0, v[138:139]
	v_pk_mul_f32 v[112:113], v[108:109], v[112:113]
	v_pk_mul_f32 v[110:111], v[106:107], v[110:111]
	v_pk_mul_f32 v[104:105], v[100:101], v[104:105]
	v_pk_mul_f32 v[102:103], v[98:99], v[102:103]
	v_pk_mul_f32 v[96:97], v[92:93], v[96:97]
	v_pk_mul_f32 v[94:95], v[90:91], v[94:95]
	v_pk_mul_f32 v[88:89], v[84:85], v[88:89]
	v_pk_mul_f32 v[86:87], v[82:83], v[86:87]
	v_pk_mul_f32 v[80:81], v[76:77], v[80:81]
	v_pk_mul_f32 v[78:79], v[74:75], v[78:79]
	v_pk_mul_f32 v[72:73], v[68:69], v[72:73]
	v_pk_mul_f32 v[70:71], v[66:67], v[70:71]
	v_pk_mul_f32 v[64:65], v[60:61], v[64:65]
	v_pk_mul_f32 v[62:63], v[58:59], v[62:63]
	v_pk_mul_f32 v[56:57], v[52:53], v[56:57]
	v_pk_mul_f32 v[54:55], v[50:51], v[54:55]
	v_pk_mul_f32 v[48:49], v[44:45], v[48:49]
	v_pk_mul_f32 v[46:47], v[42:43], v[46:47]
	v_pk_mul_f32 v[40:41], v[36:37], v[40:41]
	v_pk_mul_f32 v[38:39], v[34:35], v[38:39]
	v_pk_mul_f32 v[32:33], v[28:29], v[32:33]
	v_pk_mul_f32 v[30:31], v[26:27], v[30:31]
	v_pk_mul_f32 v[24:25], v[20:21], v[24:25]
	v_pk_mul_f32 v[22:23], v[18:19], v[22:23]
	v_pk_mul_f32 v[16:17], v[12:13], v[16:17]
	v_pk_mul_f32 v[14:15], v[10:11], v[14:15]
	v_pk_mul_f32 v[4:5], v[8:9], v[4:5]
	v_pk_mul_f32 v[2:3], v[6:7], v[2:3]
	s_and_b64 vcc, exec, s[16:17]
	s_cbranch_vccz .LBB0_155
	s_barrier
.LBB0_155:
	s_andn2_b64 vcc, exec, s[4:5]
	s_waitcnt vmcnt(0)
	v_fmamk_f32 v239, v149, 0x3a800000, v158
	v_rsq_f32_e32 v149, v239
	s_nop 0
	v_mul_f32_e32 v168, 0xbfb8aa3b, v149
	v_pk_mul_f32 v[120:121], v[120:121], v[168:169] op_sel_hi:[1,0]
	v_pk_mul_f32 v[118:119], v[118:119], v[168:169] op_sel_hi:[1,0]
	v_pk_mul_f32 v[116:117], v[116:117], v[168:169] op_sel_hi:[1,0]
	v_pk_mul_f32 v[114:115], v[114:115], v[168:169] op_sel_hi:[1,0]
	v_exp_f32_e32 v118, v118
	v_exp_f32_e32 v119, v119
	v_exp_f32_e32 v120, v120
	v_exp_f32_e32 v121, v121
	v_exp_f32_e32 v114, v114
	v_exp_f32_e32 v115, v115
	v_exp_f32_e32 v116, v116
	v_exp_f32_e32 v117, v117
	v_fma_f32 v118, v118, v239, v239
	v_fma_f32 v119, v119, v239, v239
	v_fma_f32 v120, v120, v239, v239
	v_fma_f32 v121, v121, v239, v239
	v_fma_f32 v149, v114, v239, v239
	v_fma_f32 v159, v115, v239, v239
	v_fma_f32 v163, v116, v239, v239
	v_fma_f32 v168, v117, v239, v239
	v_rcp_f32_e32 v114, v118
	v_rcp_f32_e32 v115, v119
	v_rcp_f32_e32 v116, v120
	v_rcp_f32_e32 v117, v121
	v_rcp_f32_e32 v118, v149
	v_rcp_f32_e32 v119, v159
	v_rcp_f32_e32 v120, v163
	v_rcp_f32_e32 v121, v168
	v_pk_mul_f32 v[116:117], v[128:129], v[116:117]
	v_pk_mul_f32 v[114:115], v[126:127], v[114:115]
	v_pk_mul_f32 v[120:121], v[124:125], v[120:121]
	v_pk_mul_f32 v[118:119], v[160:161], v[118:119]
	v_cvt_pk_bf16_f32 v114, v114, v115
	v_cvt_pk_bf16_f32 v115, v116, v117
	v_cvt_pk_bf16_f32 v116, v118, v119
	v_cvt_pk_bf16_f32 v117, v120, v121
	global_store_dwordx4 v[164:165], v[114:117], off
	v_fmamk_f32 v239, v232, 0x3a800000, v158
	v_rsq_f32_e32 v121, v239
	v_add_u32_e32 v114, s25, v153
	v_mul_f32_e32 v120, 0xbfb8aa3b, v121
	v_pk_mul_f32 v[108:109], v[108:109], v[120:121] op_sel_hi:[1,0]
	v_pk_mul_f32 v[106:107], v[106:107], v[120:121] op_sel_hi:[1,0]
	v_pk_mul_f32 v[100:101], v[100:101], v[120:121] op_sel_hi:[1,0]
	v_pk_mul_f32 v[98:99], v[98:99], v[120:121] op_sel_hi:[1,0]
	v_exp_f32_e32 v106, v106
	v_exp_f32_e32 v107, v107
	v_exp_f32_e32 v108, v108
	v_exp_f32_e32 v109, v109
	v_exp_f32_e32 v98, v98
	v_exp_f32_e32 v99, v99
	v_exp_f32_e32 v100, v100
	v_exp_f32_e32 v101, v101
	v_fma_f32 v106, v106, v239, v239
	v_fma_f32 v107, v107, v239, v239
	v_fma_f32 v108, v108, v239, v239
	v_fma_f32 v109, v109, v239, v239
	v_fma_f32 v115, v98, v239, v239
	v_fma_f32 v120, v99, v239, v239
	v_fma_f32 v121, v100, v239, v239
	v_fma_f32 v125, v101, v239, v239
	v_rcp_f32_e32 v98, v106
	v_rcp_f32_e32 v99, v107
	v_rcp_f32_e32 v100, v108
	v_rcp_f32_e32 v101, v109
	v_rcp_f32_e32 v106, v115
	v_rcp_f32_e32 v107, v120
	v_rcp_f32_e32 v108, v121
	v_rcp_f32_e32 v109, v125
	v_mad_i64_i32 v[116:117], s[48:49], v162, s68, v[122:123]
	v_lshl_add_u64 v[116:117], v[116:117], 0, s[46:47]
	v_pk_mul_f32 v[100:101], v[112:113], v[100:101]
	v_pk_mul_f32 v[98:99], v[110:111], v[98:99]
	v_pk_mul_f32 v[104:105], v[104:105], v[108:109]
	v_pk_mul_f32 v[102:103], v[102:103], v[106:107]
	v_lshl_add_u64 v[116:117], v[116:117], 0, v[138:139]
	v_cvt_pk_bf16_f32 v98, v98, v99
	v_cvt_pk_bf16_f32 v99, v100, v101
	v_cvt_pk_bf16_f32 v100, v102, v103
	v_cvt_pk_bf16_f32 v101, v104, v105
	global_store_dwordx4 v[116:117], v[98:101], off
	v_fmamk_f32 v239, v233, 0x3a800000, v158
	v_rsq_f32_e32 v105, v239
	v_add_u32_e32 v98, s25, v154
	v_mul_f32_e32 v104, 0xbfb8aa3b, v105
	v_pk_mul_f32 v[92:93], v[92:93], v[104:105] op_sel_hi:[1,0]
	v_pk_mul_f32 v[90:91], v[90:91], v[104:105] op_sel_hi:[1,0]
	v_pk_mul_f32 v[84:85], v[84:85], v[104:105] op_sel_hi:[1,0]
	v_pk_mul_f32 v[82:83], v[82:83], v[104:105] op_sel_hi:[1,0]
	v_exp_f32_e32 v90, v90
	v_exp_f32_e32 v91, v91
	v_exp_f32_e32 v92, v92
	v_exp_f32_e32 v93, v93
	v_exp_f32_e32 v82, v82
	v_exp_f32_e32 v83, v83
	v_exp_f32_e32 v84, v84
	v_exp_f32_e32 v85, v85
	v_fma_f32 v90, v90, v239, v239
	v_fma_f32 v91, v91, v239, v239
	v_fma_f32 v92, v92, v239, v239
	v_fma_f32 v93, v93, v239, v239
	v_fma_f32 v99, v82, v239, v239
	v_fma_f32 v104, v83, v239, v239
	v_fma_f32 v105, v84, v239, v239
	v_fma_f32 v107, v85, v239, v239
	v_rcp_f32_e32 v82, v90
	v_rcp_f32_e32 v83, v91
	v_rcp_f32_e32 v84, v92
	v_rcp_f32_e32 v85, v93
	v_rcp_f32_e32 v90, v99
	v_rcp_f32_e32 v91, v104
	v_rcp_f32_e32 v92, v105
	v_rcp_f32_e32 v93, v107
	v_mad_i64_i32 v[100:101], s[48:49], v114, s68, v[122:123]
	v_lshl_add_u64 v[100:101], v[100:101], 0, s[46:47]
	v_pk_mul_f32 v[84:85], v[96:97], v[84:85]
	v_pk_mul_f32 v[82:83], v[94:95], v[82:83]
	v_pk_mul_f32 v[88:89], v[88:89], v[92:93]
	v_pk_mul_f32 v[86:87], v[86:87], v[90:91]
	v_lshl_add_u64 v[100:101], v[100:101], 0, v[138:139]
	v_cvt_pk_bf16_f32 v82, v82, v83
	v_cvt_pk_bf16_f32 v83, v84, v85
	v_cvt_pk_bf16_f32 v84, v86, v87
	v_cvt_pk_bf16_f32 v85, v88, v89
	global_store_dwordx4 v[100:101], v[82:85], off
	s_nop 0
	s_nop 0
	v_add_u32_e32 v84, 0x80, v148
	v_mad_i64_i32 v[82:83], s[48:49], v98, s68, v[122:123]
	v_lshl_add_u64 v[82:83], v[82:83], 0, s[46:47]
	v_lshl_add_u64 v[82:83], v[82:83], 0, v[138:139]
	v_fmamk_f32 v239, v234, 0x3a800000, v158
	v_rsq_f32_e32 v89, v239
	s_nop 0
	v_mul_f32_e32 v88, 0xbfb8aa3b, v89
	v_pk_mul_f32 v[76:77], v[76:77], v[88:89] op_sel_hi:[1,0]
	v_pk_mul_f32 v[74:75], v[74:75], v[88:89] op_sel_hi:[1,0]
	v_pk_mul_f32 v[68:69], v[68:69], v[88:89] op_sel_hi:[1,0]
	v_pk_mul_f32 v[66:67], v[66:67], v[88:89] op_sel_hi:[1,0]
	v_exp_f32_e32 v74, v74
	v_exp_f32_e32 v75, v75
	v_exp_f32_e32 v76, v76
	v_exp_f32_e32 v77, v77
	v_exp_f32_e32 v66, v66
	v_exp_f32_e32 v67, v67
	v_exp_f32_e32 v68, v68
	v_exp_f32_e32 v69, v69
	v_fma_f32 v74, v74, v239, v239
	v_fma_f32 v75, v75, v239, v239
	v_fma_f32 v76, v76, v239, v239
	v_fma_f32 v77, v77, v239, v239
	v_fma_f32 v85, v66, v239, v239
	v_fma_f32 v88, v67, v239, v239
	v_fma_f32 v89, v68, v239, v239
	v_fma_f32 v91, v69, v239, v239
	v_rcp_f32_e32 v66, v74
	v_rcp_f32_e32 v67, v75
	v_rcp_f32_e32 v68, v76
	v_rcp_f32_e32 v69, v77
	v_rcp_f32_e32 v74, v85
	v_rcp_f32_e32 v75, v88
	v_rcp_f32_e32 v76, v89
	v_rcp_f32_e32 v77, v91
	v_pk_mul_f32 v[68:69], v[80:81], v[68:69]
	v_pk_mul_f32 v[66:67], v[78:79], v[66:67]
	v_pk_mul_f32 v[72:73], v[72:73], v[76:77]
	v_pk_mul_f32 v[70:71], v[70:71], v[74:75]
	v_cvt_pk_bf16_f32 v66, v66, v67
	v_cvt_pk_bf16_f32 v67, v68, v69
	v_cvt_pk_bf16_f32 v68, v70, v71
	v_cvt_pk_bf16_f32 v69, v72, v73
	global_store_dwordx4 v[82:83], v[66:69], off
	v_fmamk_f32 v239, v235, 0x3a800000, v158
	v_rsq_f32_e32 v73, v239
	v_add_u32_e32 v66, 0x90, v148
	v_mul_f32_e32 v72, 0xbfb8aa3b, v73
	v_pk_mul_f32 v[60:61], v[60:61], v[72:73] op_sel_hi:[1,0]
	v_pk_mul_f32 v[58:59], v[58:59], v[72:73] op_sel_hi:[1,0]
	v_pk_mul_f32 v[52:53], v[52:53], v[72:73] op_sel_hi:[1,0]
	v_pk_mul_f32 v[50:51], v[50:51], v[72:73] op_sel_hi:[1,0]
	v_exp_f32_e32 v58, v58
	v_exp_f32_e32 v59, v59
	v_exp_f32_e32 v60, v60
	v_exp_f32_e32 v61, v61
	v_exp_f32_e32 v50, v50
	v_exp_f32_e32 v51, v51
	v_exp_f32_e32 v52, v52
	v_exp_f32_e32 v53, v53
	v_fma_f32 v58, v58, v239, v239
	v_fma_f32 v59, v59, v239, v239
	v_fma_f32 v60, v60, v239, v239
	v_fma_f32 v61, v61, v239, v239
	v_fma_f32 v67, v50, v239, v239
	v_fma_f32 v72, v51, v239, v239
	v_fma_f32 v73, v52, v239, v239
	v_fma_f32 v75, v53, v239, v239
	v_rcp_f32_e32 v50, v58
	v_rcp_f32_e32 v51, v59
	v_rcp_f32_e32 v52, v60
	v_rcp_f32_e32 v53, v61
	v_rcp_f32_e32 v58, v67
	v_rcp_f32_e32 v59, v72
	v_rcp_f32_e32 v60, v73
	v_rcp_f32_e32 v61, v75
	v_mad_i64_i32 v[68:69], s[48:49], v84, s68, v[122:123]
	v_lshl_add_u64 v[68:69], v[68:69], 0, s[46:47]
	v_pk_mul_f32 v[52:53], v[64:65], v[52:53]
	v_pk_mul_f32 v[50:51], v[62:63], v[50:51]
	v_pk_mul_f32 v[56:57], v[56:57], v[60:61]
	v_pk_mul_f32 v[54:55], v[54:55], v[58:59]
	v_lshl_add_u64 v[68:69], v[68:69], 0, v[138:139]
	v_cvt_pk_bf16_f32 v50, v50, v51
	v_cvt_pk_bf16_f32 v51, v52, v53
	v_cvt_pk_bf16_f32 v52, v54, v55
	v_cvt_pk_bf16_f32 v53, v56, v57
	global_store_dwordx4 v[68:69], v[50:53], off
	v_fmamk_f32 v239, v236, 0x3a800000, v158
	v_rsq_f32_e32 v57, v239
	v_add_u32_e32 v50, 0xa0, v148
	v_mul_f32_e32 v56, 0xbfb8aa3b, v57
	v_pk_mul_f32 v[44:45], v[44:45], v[56:57] op_sel_hi:[1,0]
	v_pk_mul_f32 v[42:43], v[42:43], v[56:57] op_sel_hi:[1,0]
	v_pk_mul_f32 v[36:37], v[36:37], v[56:57] op_sel_hi:[1,0]
	v_pk_mul_f32 v[34:35], v[34:35], v[56:57] op_sel_hi:[1,0]
	v_exp_f32_e32 v42, v42
	v_exp_f32_e32 v43, v43
	v_exp_f32_e32 v44, v44
	v_exp_f32_e32 v45, v45
	v_exp_f32_e32 v34, v34
	v_exp_f32_e32 v35, v35
	v_exp_f32_e32 v36, v36
	v_exp_f32_e32 v37, v37
	v_fma_f32 v42, v42, v239, v239
	v_fma_f32 v43, v43, v239, v239
	v_fma_f32 v44, v44, v239, v239
	v_fma_f32 v45, v45, v239, v239
	v_fma_f32 v51, v34, v239, v239
	v_fma_f32 v56, v35, v239, v239
	v_fma_f32 v57, v36, v239, v239
	v_fma_f32 v59, v37, v239, v239
	v_rcp_f32_e32 v34, v42
	v_rcp_f32_e32 v35, v43
	v_rcp_f32_e32 v36, v44
	v_rcp_f32_e32 v37, v45
	v_rcp_f32_e32 v42, v51
	v_rcp_f32_e32 v43, v56
	v_rcp_f32_e32 v44, v57
	v_rcp_f32_e32 v45, v59
	v_mad_i64_i32 v[52:53], s[48:49], v66, s68, v[122:123]
	v_lshl_add_u64 v[52:53], v[52:53], 0, s[46:47]
	v_pk_mul_f32 v[36:37], v[48:49], v[36:37]
	v_pk_mul_f32 v[34:35], v[46:47], v[34:35]
	v_pk_mul_f32 v[40:41], v[40:41], v[44:45]
	v_pk_mul_f32 v[38:39], v[38:39], v[42:43]
	v_lshl_add_u64 v[52:53], v[52:53], 0, v[138:139]
	v_cvt_pk_bf16_f32 v34, v34, v35
	v_cvt_pk_bf16_f32 v35, v36, v37
	v_cvt_pk_bf16_f32 v36, v38, v39
	v_cvt_pk_bf16_f32 v37, v40, v41
	global_store_dwordx4 v[52:53], v[34:37], off
	v_fmamk_f32 v239, v237, 0x3a800000, v158
	v_rsq_f32_e32 v41, v239
	v_add_u32_e32 v34, 0xb0, v148
	v_mul_f32_e32 v40, 0xbfb8aa3b, v41
	v_pk_mul_f32 v[28:29], v[28:29], v[40:41] op_sel_hi:[1,0]
	v_pk_mul_f32 v[26:27], v[26:27], v[40:41] op_sel_hi:[1,0]
	v_pk_mul_f32 v[20:21], v[20:21], v[40:41] op_sel_hi:[1,0]
	v_pk_mul_f32 v[18:19], v[18:19], v[40:41] op_sel_hi:[1,0]
	v_exp_f32_e32 v26, v26
	v_exp_f32_e32 v27, v27
	v_exp_f32_e32 v28, v28
	v_exp_f32_e32 v29, v29
	v_exp_f32_e32 v18, v18
	v_exp_f32_e32 v19, v19
	v_exp_f32_e32 v20, v20
	v_exp_f32_e32 v21, v21
	v_fma_f32 v26, v26, v239, v239
	v_fma_f32 v27, v27, v239, v239
	v_fma_f32 v28, v28, v239, v239
	v_fma_f32 v29, v29, v239, v239
	v_fma_f32 v35, v18, v239, v239
	v_fma_f32 v40, v19, v239, v239
	v_fma_f32 v41, v20, v239, v239
	v_fma_f32 v43, v21, v239, v239
	v_rcp_f32_e32 v18, v26
	v_rcp_f32_e32 v19, v27
	v_rcp_f32_e32 v20, v28
	v_rcp_f32_e32 v21, v29
	v_rcp_f32_e32 v26, v35
	v_rcp_f32_e32 v27, v40
	v_rcp_f32_e32 v28, v41
	v_rcp_f32_e32 v29, v43
	v_mad_i64_i32 v[36:37], s[48:49], v50, s68, v[122:123]
	v_lshl_add_u64 v[36:37], v[36:37], 0, s[46:47]
	v_pk_mul_f32 v[20:21], v[32:33], v[20:21]
	v_pk_mul_f32 v[18:19], v[30:31], v[18:19]
	v_pk_mul_f32 v[24:25], v[24:25], v[28:29]
	v_pk_mul_f32 v[22:23], v[22:23], v[26:27]
	v_lshl_add_u64 v[36:37], v[36:37], 0, v[138:139]
	v_cvt_pk_bf16_f32 v18, v18, v19
	v_cvt_pk_bf16_f32 v19, v20, v21
	v_cvt_pk_bf16_f32 v20, v22, v23
	v_cvt_pk_bf16_f32 v21, v24, v25
	global_store_dwordx4 v[36:37], v[18:21], off
	s_nop 0
	s_nop 0
	v_fmamk_f32 v239, v238, 0x3a800000, v158
	v_rsq_f32_e32 v21, v239
	v_mad_i64_i32 v[18:19], s[4:5], v34, s68, v[122:123]
	v_lshl_add_u64 v[18:19], v[18:19], 0, s[46:47]
	v_mul_f32_e32 v20, 0xbfb8aa3b, v21
	v_pk_mul_f32 v[12:13], v[12:13], v[20:21] op_sel_hi:[1,0]
	v_pk_mul_f32 v[10:11], v[10:11], v[20:21] op_sel_hi:[1,0]
	v_pk_mul_f32 v[8:9], v[8:9], v[20:21] op_sel_hi:[1,0]
	v_pk_mul_f32 v[6:7], v[6:7], v[20:21] op_sel_hi:[1,0]
	v_exp_f32_e32 v10, v10
	v_exp_f32_e32 v11, v11
	v_exp_f32_e32 v12, v12
	v_exp_f32_e32 v13, v13
	v_exp_f32_e32 v6, v6
	v_exp_f32_e32 v7, v7
	v_exp_f32_e32 v8, v8
	v_exp_f32_e32 v9, v9
	v_fma_f32 v10, v10, v239, v239
	v_fma_f32 v11, v11, v239, v239
	v_fma_f32 v12, v12, v239, v239
	v_fma_f32 v13, v13, v239, v239
	v_fma_f32 v20, v6, v239, v239
	v_fma_f32 v21, v7, v239, v239
	v_fma_f32 v23, v8, v239, v239
	v_fma_f32 v24, v9, v239, v239
	v_rcp_f32_e32 v6, v10
	v_rcp_f32_e32 v7, v11
	v_rcp_f32_e32 v8, v12
	v_rcp_f32_e32 v9, v13
	v_rcp_f32_e32 v10, v20
	v_rcp_f32_e32 v11, v21
	v_rcp_f32_e32 v12, v23
	v_rcp_f32_e32 v13, v24
	v_pk_mul_f32 v[8:9], v[16:17], v[8:9]
	v_pk_mul_f32 v[6:7], v[14:15], v[6:7]
	v_pk_mul_f32 v[12:13], v[4:5], v[12:13]
	v_pk_mul_f32 v[4:5], v[2:3], v[10:11]
	v_lshl_add_u64 v[18:19], v[18:19], 0, v[138:139]
	v_cvt_pk_bf16_f32 v2, v6, v7
	v_cvt_pk_bf16_f32 v3, v8, v9
	v_cvt_pk_bf16_f32 v4, v4, v5
	v_cvt_pk_bf16_f32 v5, v12, v13
	s_mov_b64 s[4:5], -1
	global_store_dwordx4 v[18:19], v[2:5], off
	s_cbranch_vccnz .LBB0_148
	s_andn2_b64 vcc, exec, s[10:11]
	s_cbranch_vccnz .LBB0_147
	s_barrier
	s_branch .LBB0_147

.LBB0_245:
	s_ashr_i32 s6, s42, 3
	s_add_i32 s6, s48, s6
	s_ashr_i32 s7, s6, 31
	s_lshr_b32 s7, s7, 27
	s_add_i32 s7, s6, s7
	s_ashr_i32 s42, s7, 5
	s_lshl_b32 s42, s42, 3
	s_andn2_b32 s7, s7, 31
	s_sub_i32 s6, s6, s7
	s_lshr_b32 s65, s6, 3
	s_and_b32 s6, s6, 7
	s_add_i32 s66, s42, s6

.LBB0_349:
	s_add_i32 s69, s69, 1
	s_mul_i32 s4, s69, s65
	s_mul_hi_u32 s5, s69, s66
	s_add_i32 s5, s5, s4
	s_mul_i32 s4, s69, s66
	s_add_u32 s44, s4, s2
	s_addc_u32 s45, s5, s55
	v_cmp_gt_i64_e32 vcc, s[44:45], v[146:147]
	v_cmp_lt_i64_e64 s[4:5], s[44:45], v[144:145]
	s_cbranch_vccnz .LBB0_351
	s_ashr_i32 s7, s44, 31
	s_lshr_b32 s7, s7, 29
	s_add_i32 s7, s44, s7
	s_ashr_i32 s26, s7, 3
	s_and_b32 s7, s7, -8
	s_sub_i32 s7, s44, s7
	s_cmp_lt_i32 s7, 0
	s_cselect_b32 s27, s56, 0xc0
	s_mul_i32 s7, s7, s27
	s_add_i32 s7, s7, s26
	s_mul_hi_i32 s26, s7, 0x2aaaaaab
	s_lshr_b32 s27, s26, 31
	s_ashr_i32 s26, s26, 4
	s_add_i32 s26, s26, s27
	s_lshl_b32 s27, s26, 3
	s_mulk_i32 s26, 0x60
	s_sub_i32 s7, s7, s26
	s_lshr_b32 s26, s7, 3
	s_and_b32 s7, s7, 7
	s_add_i32 s42, s27, s7

.LBB0_737:
	s_ashr_i32 s26, s42, 3
	s_add_i32 s26, s44, s26
	s_ashr_i32 s27, s26, 31
	s_lshr_b32 s27, s27, 27
	s_add_i32 s27, s26, s27
	s_ashr_i32 s42, s27, 5
	s_lshl_b32 s42, s42, 3
	s_andn2_b32 s27, s27, 31
	s_sub_i32 s27, s26, s27
	s_lshr_b32 s26, s27, 3
	s_and_b32 s27, s27, 7
	s_add_i32 s42, s42, s27

.Lz_post_p6:
	s_lshl_b32 s25, s46, 8
	v_add_u32_e32 v148, s25, v150
	v_ashrrev_i32_e32 v149, 31, v148
	v_lshl_add_u64 v[160:161], v[148:149], 2, s[10:11]
	global_load_dword v149, v[160:161], off
	global_load_dword v232, v[160:161], off offset:64
	global_load_dword v233, v[160:161], off offset:128
	global_load_dword v234, v[160:161], off offset:192
	global_load_dword v235, v[160:161], off offset:512
	global_load_dword v236, v[160:161], off offset:576
	global_load_dword v237, v[160:161], off offset:640
	global_load_dword v238, v[160:161], off offset:704
	v_pk_mul_f32 v[128:129], v[120:121], v[128:129]
	v_pk_mul_f32 v[126:127], v[118:119], v[126:127]
	v_pk_mul_f32 v[124:125], v[116:117], v[124:125]
	v_pk_mul_f32 v[160:161], v[114:115], v[122:123]
	v_add_u32_e32 v162, s25, v152
	s_lshl_b32 s46, s47, 7
	v_mov_b64_e32 v[122:123], s[12:13]
	s_ashr_i32 s47, s46, 31
	v_mad_i64_i32 v[164:165], s[48:49], v148, s68, v[122:123]
	s_lshl_b64 s[46:47], s[46:47], 1
	v_lshl_add_u64 v[164:165], v[164:165], 0, s[46:47]
	v_lshl_add_u64 v[164:165], v[164:165], 0, v[138:139]
	v_pk_mul_f32 v[112:113], v[108:109], v[112:113]
	v_pk_mul_f32 v[110:111], v[106:107], v[110:111]
	v_pk_mul_f32 v[104:105], v[100:101], v[104:105]
	v_pk_mul_f32 v[102:103], v[98:99], v[102:103]
	v_pk_mul_f32 v[96:97], v[92:93], v[96:97]
	v_pk_mul_f32 v[94:95], v[90:91], v[94:95]
	v_pk_mul_f32 v[88:89], v[84:85], v[88:89]
	v_pk_mul_f32 v[86:87], v[82:83], v[86:87]
	v_pk_mul_f32 v[80:81], v[76:77], v[80:81]
	v_pk_mul_f32 v[78:79], v[74:75], v[78:79]
	v_pk_mul_f32 v[72:73], v[68:69], v[72:73]
	v_pk_mul_f32 v[70:71], v[66:67], v[70:71]
	v_pk_mul_f32 v[64:65], v[60:61], v[64:65]
	v_pk_mul_f32 v[62:63], v[58:59], v[62:63]
	v_pk_mul_f32 v[56:57], v[52:53], v[56:57]
	v_pk_mul_f32 v[54:55], v[50:51], v[54:55]
	v_pk_mul_f32 v[48:49], v[44:45], v[48:49]
	v_pk_mul_f32 v[46:47], v[42:43], v[46:47]
	v_pk_mul_f32 v[40:41], v[36:37], v[40:41]
	v_pk_mul_f32 v[38:39], v[34:35], v[38:39]
	v_pk_mul_f32 v[32:33], v[28:29], v[32:33]
	v_pk_mul_f32 v[30:31], v[26:27], v[30:31]
	v_pk_mul_f32 v[24:25], v[20:21], v[24:25]
	v_pk_mul_f32 v[22:23], v[18:19], v[22:23]
	v_pk_mul_f32 v[16:17], v[12:13], v[16:17]
	v_pk_mul_f32 v[14:15], v[10:11], v[14:15]
	v_pk_mul_f32 v[4:5], v[8:9], v[4:5]
	v_pk_mul_f32 v[2:3], v[6:7], v[2:3]
	s_and_b64 vcc, exec, s[16:17]
	s_cbranch_vccz .LBB0_843
	s_barrier
.LBB0_843:
	s_andn2_b64 vcc, exec, s[4:5]
	s_waitcnt vmcnt(0)
	v_fmamk_f32 v239, v149, 0x3a800000, v158
	v_rsq_f32_e32 v149, v239
	s_nop 0
	v_mul_f32_e32 v168, 0xbfb8aa3b, v149
	v_pk_mul_f32 v[120:121], v[120:121], v[168:169] op_sel_hi:[1,0]
	v_pk_mul_f32 v[118:119], v[118:119], v[168:169] op_sel_hi:[1,0]
	v_pk_mul_f32 v[116:117], v[116:117], v[168:169] op_sel_hi:[1,0]
	v_pk_mul_f32 v[114:115], v[114:115], v[168:169] op_sel_hi:[1,0]
	v_exp_f32_e32 v118, v118
	v_exp_f32_e32 v119, v119
	v_exp_f32_e32 v120, v120
	v_exp_f32_e32 v121, v121
	v_exp_f32_e32 v114, v114
	v_exp_f32_e32 v115, v115
	v_exp_f32_e32 v116, v116
	v_exp_f32_e32 v117, v117
	v_fma_f32 v118, v118, v239, v239
	v_fma_f32 v119, v119, v239, v239
	v_fma_f32 v120, v120, v239, v239
	v_fma_f32 v121, v121, v239, v239
	v_fma_f32 v149, v114, v239, v239
	v_fma_f32 v159, v115, v239, v239
	v_fma_f32 v163, v116, v239, v239
	v_fma_f32 v168, v117, v239, v239
	v_rcp_f32_e32 v114, v118
	v_rcp_f32_e32 v115, v119
	v_rcp_f32_e32 v116, v120
	v_rcp_f32_e32 v117, v121
	v_rcp_f32_e32 v118, v149
	v_rcp_f32_e32 v119, v159
	v_rcp_f32_e32 v120, v163
	v_rcp_f32_e32 v121, v168
	v_pk_mul_f32 v[116:117], v[128:129], v[116:117]
	v_pk_mul_f32 v[114:115], v[126:127], v[114:115]
	v_pk_mul_f32 v[120:121], v[124:125], v[120:121]
	v_pk_mul_f32 v[118:119], v[160:161], v[118:119]
	v_cvt_pk_bf16_f32 v114, v114, v115
	v_cvt_pk_bf16_f32 v115, v116, v117
	v_cvt_pk_bf16_f32 v116, v118, v119
	v_cvt_pk_bf16_f32 v117, v120, v121
	global_store_dwordx4 v[164:165], v[114:117], off
	v_fmamk_f32 v239, v232, 0x3a800000, v158
	v_rsq_f32_e32 v121, v239
	v_add_u32_e32 v114, s25, v153
	v_mul_f32_e32 v120, 0xbfb8aa3b, v121
	v_pk_mul_f32 v[108:109], v[108:109], v[120:121] op_sel_hi:[1,0]
	v_pk_mul_f32 v[106:107], v[106:107], v[120:121] op_sel_hi:[1,0]
	v_pk_mul_f32 v[100:101], v[100:101], v[120:121] op_sel_hi:[1,0]
	v_pk_mul_f32 v[98:99], v[98:99], v[120:121] op_sel_hi:[1,0]
	v_exp_f32_e32 v106, v106
	v_exp_f32_e32 v107, v107
	v_exp_f32_e32 v108, v108
	v_exp_f32_e32 v109, v109
	v_exp_f32_e32 v98, v98
	v_exp_f32_e32 v99, v99
	v_exp_f32_e32 v100, v100
	v_exp_f32_e32 v101, v101
	v_fma_f32 v106, v106, v239, v239
	v_fma_f32 v107, v107, v239, v239
	v_fma_f32 v108, v108, v239, v239
	v_fma_f32 v109, v109, v239, v239
	v_fma_f32 v115, v98, v239, v239
	v_fma_f32 v120, v99, v239, v239
	v_fma_f32 v121, v100, v239, v239
	v_fma_f32 v125, v101, v239, v239
	v_rcp_f32_e32 v98, v106
	v_rcp_f32_e32 v99, v107
	v_rcp_f32_e32 v100, v108
	v_rcp_f32_e32 v101, v109
	v_rcp_f32_e32 v106, v115
	v_rcp_f32_e32 v107, v120
	v_rcp_f32_e32 v108, v121
	v_rcp_f32_e32 v109, v125
	v_mad_i64_i32 v[116:117], s[48:49], v162, s68, v[122:123]
	v_lshl_add_u64 v[116:117], v[116:117], 0, s[46:47]
	v_pk_mul_f32 v[100:101], v[112:113], v[100:101]
	v_pk_mul_f32 v[98:99], v[110:111], v[98:99]
	v_pk_mul_f32 v[104:105], v[104:105], v[108:109]
	v_pk_mul_f32 v[102:103], v[102:103], v[106:107]
	v_lshl_add_u64 v[116:117], v[116:117], 0, v[138:139]
	v_cvt_pk_bf16_f32 v98, v98, v99
	v_cvt_pk_bf16_f32 v99, v100, v101
	v_cvt_pk_bf16_f32 v100, v102, v103
	v_cvt_pk_bf16_f32 v101, v104, v105
	global_store_dwordx4 v[116:117], v[98:101], off
	v_fmamk_f32 v239, v233, 0x3a800000, v158
	v_rsq_f32_e32 v105, v239
	v_add_u32_e32 v98, s25, v154
	v_mul_f32_e32 v104, 0xbfb8aa3b, v105
	v_pk_mul_f32 v[92:93], v[92:93], v[104:105] op_sel_hi:[1,0]
	v_pk_mul_f32 v[90:91], v[90:91], v[104:105] op_sel_hi:[1,0]
	v_pk_mul_f32 v[84:85], v[84:85], v[104:105] op_sel_hi:[1,0]
	v_pk_mul_f32 v[82:83], v[82:83], v[104:105] op_sel_hi:[1,0]
	v_exp_f32_e32 v90, v90
	v_exp_f32_e32 v91, v91
	v_exp_f32_e32 v92, v92
	v_exp_f32_e32 v93, v93
	v_exp_f32_e32 v82, v82
	v_exp_f32_e32 v83, v83
	v_exp_f32_e32 v84, v84
	v_exp_f32_e32 v85, v85
	v_fma_f32 v90, v90, v239, v239
	v_fma_f32 v91, v91, v239, v239
	v_fma_f32 v92, v92, v239, v239
	v_fma_f32 v93, v93, v239, v239
	v_fma_f32 v99, v82, v239, v239
	v_fma_f32 v104, v83, v239, v239
	v_fma_f32 v105, v84, v239, v239
	v_fma_f32 v107, v85, v239, v239
	v_rcp_f32_e32 v82, v90
	v_rcp_f32_e32 v83, v91
	v_rcp_f32_e32 v84, v92
	v_rcp_f32_e32 v85, v93
	v_rcp_f32_e32 v90, v99
	v_rcp_f32_e32 v91, v104
	v_rcp_f32_e32 v92, v105
	v_rcp_f32_e32 v93, v107
	v_mad_i64_i32 v[100:101], s[48:49], v114, s68, v[122:123]
	v_lshl_add_u64 v[100:101], v[100:101], 0, s[46:47]
	v_pk_mul_f32 v[84:85], v[96:97], v[84:85]
	v_pk_mul_f32 v[82:83], v[94:95], v[82:83]
	v_pk_mul_f32 v[88:89], v[88:89], v[92:93]
	v_pk_mul_f32 v[86:87], v[86:87], v[90:91]
	v_lshl_add_u64 v[100:101], v[100:101], 0, v[138:139]
	v_cvt_pk_bf16_f32 v82, v82, v83
	v_cvt_pk_bf16_f32 v83, v84, v85
	v_cvt_pk_bf16_f32 v84, v86, v87
	v_cvt_pk_bf16_f32 v85, v88, v89
	global_store_dwordx4 v[100:101], v[82:85], off
	s_nop 0
	s_nop 0
	v_add_u32_e32 v84, 0x80, v148
	v_mad_i64_i32 v[82:83], s[48:49], v98, s68, v[122:123]
	v_lshl_add_u64 v[82:83], v[82:83], 0, s[46:47]
	v_lshl_add_u64 v[82:83], v[82:83], 0, v[138:139]
	v_fmamk_f32 v239, v234, 0x3a800000, v158
	v_rsq_f32_e32 v89, v239
	s_nop 0
	v_mul_f32_e32 v88, 0xbfb8aa3b, v89
	v_pk_mul_f32 v[76:77], v[76:77], v[88:89] op_sel_hi:[1,0]
	v_pk_mul_f32 v[74:75], v[74:75], v[88:89] op_sel_hi:[1,0]
	v_pk_mul_f32 v[68:69], v[68:69], v[88:89] op_sel_hi:[1,0]
	v_pk_mul_f32 v[66:67], v[66:67], v[88:89] op_sel_hi:[1,0]
	v_exp_f32_e32 v74, v74
	v_exp_f32_e32 v75, v75
	v_exp_f32_e32 v76, v76
	v_exp_f32_e32 v77, v77
	v_exp_f32_e32 v66, v66
	v_exp_f32_e32 v67, v67
	v_exp_f32_e32 v68, v68
	v_exp_f32_e32 v69, v69
	v_fma_f32 v74, v74, v239, v239
	v_fma_f32 v75, v75, v239, v239
	v_fma_f32 v76, v76, v239, v239
	v_fma_f32 v77, v77, v239, v239
	v_fma_f32 v85, v66, v239, v239
	v_fma_f32 v88, v67, v239, v239
	v_fma_f32 v89, v68, v239, v239
	v_fma_f32 v91, v69, v239, v239
	v_rcp_f32_e32 v66, v74
	v_rcp_f32_e32 v67, v75
	v_rcp_f32_e32 v68, v76
	v_rcp_f32_e32 v69, v77
	v_rcp_f32_e32 v74, v85
	v_rcp_f32_e32 v75, v88
	v_rcp_f32_e32 v76, v89
	v_rcp_f32_e32 v77, v91
	v_pk_mul_f32 v[68:69], v[80:81], v[68:69]
	v_pk_mul_f32 v[66:67], v[78:79], v[66:67]
	v_pk_mul_f32 v[72:73], v[72:73], v[76:77]
	v_pk_mul_f32 v[70:71], v[70:71], v[74:75]
	v_cvt_pk_bf16_f32 v66, v66, v67
	v_cvt_pk_bf16_f32 v67, v68, v69
	v_cvt_pk_bf16_f32 v68, v70, v71
	v_cvt_pk_bf16_f32 v69, v72, v73
	global_store_dwordx4 v[82:83], v[66:69], off
	v_fmamk_f32 v239, v235, 0x3a800000, v158
	v_rsq_f32_e32 v73, v239
	v_add_u32_e32 v66, 0x90, v148
	v_mul_f32_e32 v72, 0xbfb8aa3b, v73
	v_pk_mul_f32 v[60:61], v[60:61], v[72:73] op_sel_hi:[1,0]
	v_pk_mul_f32 v[58:59], v[58:59], v[72:73] op_sel_hi:[1,0]
	v_pk_mul_f32 v[52:53], v[52:53], v[72:73] op_sel_hi:[1,0]
	v_pk_mul_f32 v[50:51], v[50:51], v[72:73] op_sel_hi:[1,0]
	v_exp_f32_e32 v58, v58
	v_exp_f32_e32 v59, v59
	v_exp_f32_e32 v60, v60
	v_exp_f32_e32 v61, v61
	v_exp_f32_e32 v50, v50
	v_exp_f32_e32 v51, v51
	v_exp_f32_e32 v52, v52
	v_exp_f32_e32 v53, v53
	v_fma_f32 v58, v58, v239, v239
	v_fma_f32 v59, v59, v239, v239
	v_fma_f32 v60, v60, v239, v239
	v_fma_f32 v61, v61, v239, v239
	v_fma_f32 v67, v50, v239, v239
	v_fma_f32 v72, v51, v239, v239
	v_fma_f32 v73, v52, v239, v239
	v_fma_f32 v75, v53, v239, v239
	v_rcp_f32_e32 v50, v58
	v_rcp_f32_e32 v51, v59
	v_rcp_f32_e32 v52, v60
	v_rcp_f32_e32 v53, v61
	v_rcp_f32_e32 v58, v67
	v_rcp_f32_e32 v59, v72
	v_rcp_f32_e32 v60, v73
	v_rcp_f32_e32 v61, v75
	v_mad_i64_i32 v[68:69], s[48:49], v84, s68, v[122:123]
	v_lshl_add_u64 v[68:69], v[68:69], 0, s[46:47]
	v_pk_mul_f32 v[52:53], v[64:65], v[52:53]
	v_pk_mul_f32 v[50:51], v[62:63], v[50:51]
	v_pk_mul_f32 v[56:57], v[56:57], v[60:61]
	v_pk_mul_f32 v[54:55], v[54:55], v[58:59]
	v_lshl_add_u64 v[68:69], v[68:69], 0, v[138:139]
	v_cvt_pk_bf16_f32 v50, v50, v51
	v_cvt_pk_bf16_f32 v51, v52, v53
	v_cvt_pk_bf16_f32 v52, v54, v55
	v_cvt_pk_bf16_f32 v53, v56, v57
	global_store_dwordx4 v[68:69], v[50:53], off
	v_fmamk_f32 v239, v236, 0x3a800000, v158
	v_rsq_f32_e32 v57, v239
	v_add_u32_e32 v50, 0xa0, v148
	v_mul_f32_e32 v56, 0xbfb8aa3b, v57
	v_pk_mul_f32 v[44:45], v[44:45], v[56:57] op_sel_hi:[1,0]
	v_pk_mul_f32 v[42:43], v[42:43], v[56:57] op_sel_hi:[1,0]
	v_pk_mul_f32 v[36:37], v[36:37], v[56:57] op_sel_hi:[1,0]
	v_pk_mul_f32 v[34:35], v[34:35], v[56:57] op_sel_hi:[1,0]
	v_exp_f32_e32 v42, v42
	v_exp_f32_e32 v43, v43
	v_exp_f32_e32 v44, v44
	v_exp_f32_e32 v45, v45
	v_exp_f32_e32 v34, v34
	v_exp_f32_e32 v35, v35
	v_exp_f32_e32 v36, v36
	v_exp_f32_e32 v37, v37
	v_fma_f32 v42, v42, v239, v239
	v_fma_f32 v43, v43, v239, v239
	v_fma_f32 v44, v44, v239, v239
	v_fma_f32 v45, v45, v239, v239
	v_fma_f32 v51, v34, v239, v239
	v_fma_f32 v56, v35, v239, v239
	v_fma_f32 v57, v36, v239, v239
	v_fma_f32 v59, v37, v239, v239
	v_rcp_f32_e32 v34, v42
	v_rcp_f32_e32 v35, v43
	v_rcp_f32_e32 v36, v44
	v_rcp_f32_e32 v37, v45
	v_rcp_f32_e32 v42, v51
	v_rcp_f32_e32 v43, v56
	v_rcp_f32_e32 v44, v57
	v_rcp_f32_e32 v45, v59
	v_mad_i64_i32 v[52:53], s[48:49], v66, s68, v[122:123]
	v_lshl_add_u64 v[52:53], v[52:53], 0, s[46:47]
	v_pk_mul_f32 v[36:37], v[48:49], v[36:37]
	v_pk_mul_f32 v[34:35], v[46:47], v[34:35]
	v_pk_mul_f32 v[40:41], v[40:41], v[44:45]
	v_pk_mul_f32 v[38:39], v[38:39], v[42:43]
	v_lshl_add_u64 v[52:53], v[52:53], 0, v[138:139]
	v_cvt_pk_bf16_f32 v34, v34, v35
	v_cvt_pk_bf16_f32 v35, v36, v37
	v_cvt_pk_bf16_f32 v36, v38, v39
	v_cvt_pk_bf16_f32 v37, v40, v41
	global_store_dwordx4 v[52:53], v[34:37], off
	v_fmamk_f32 v239, v237, 0x3a800000, v158
	v_rsq_f32_e32 v41, v239
	v_add_u32_e32 v34, 0xb0, v148
	v_mul_f32_e32 v40, 0xbfb8aa3b, v41
	v_pk_mul_f32 v[28:29], v[28:29], v[40:41] op_sel_hi:[1,0]
	v_pk_mul_f32 v[26:27], v[26:27], v[40:41] op_sel_hi:[1,0]
	v_pk_mul_f32 v[20:21], v[20:21], v[40:41] op_sel_hi:[1,0]
	v_pk_mul_f32 v[18:19], v[18:19], v[40:41] op_sel_hi:[1,0]
	v_exp_f32_e32 v26, v26
	v_exp_f32_e32 v27, v27
	v_exp_f32_e32 v28, v28
	v_exp_f32_e32 v29, v29
	v_exp_f32_e32 v18, v18
	v_exp_f32_e32 v19, v19
	v_exp_f32_e32 v20, v20
	v_exp_f32_e32 v21, v21
	v_fma_f32 v26, v26, v239, v239
	v_fma_f32 v27, v27, v239, v239
	v_fma_f32 v28, v28, v239, v239
	v_fma_f32 v29, v29, v239, v239
	v_fma_f32 v35, v18, v239, v239
	v_fma_f32 v40, v19, v239, v239
	v_fma_f32 v41, v20, v239, v239
	v_fma_f32 v43, v21, v239, v239
	v_rcp_f32_e32 v18, v26
	v_rcp_f32_e32 v19, v27
	v_rcp_f32_e32 v20, v28
	v_rcp_f32_e32 v21, v29
	v_rcp_f32_e32 v26, v35
	v_rcp_f32_e32 v27, v40
	v_rcp_f32_e32 v28, v41
	v_rcp_f32_e32 v29, v43
	v_mad_i64_i32 v[36:37], s[48:49], v50, s68, v[122:123]
	v_lshl_add_u64 v[36:37], v[36:37], 0, s[46:47]
	v_pk_mul_f32 v[20:21], v[32:33], v[20:21]
	v_pk_mul_f32 v[18:19], v[30:31], v[18:19]
	v_pk_mul_f32 v[24:25], v[24:25], v[28:29]
	v_pk_mul_f32 v[22:23], v[22:23], v[26:27]
	v_lshl_add_u64 v[36:37], v[36:37], 0, v[138:139]
	v_cvt_pk_bf16_f32 v18, v18, v19
	v_cvt_pk_bf16_f32 v19, v20, v21
	v_cvt_pk_bf16_f32 v20, v22, v23
	v_cvt_pk_bf16_f32 v21, v24, v25
	global_store_dwordx4 v[36:37], v[18:21], off
	s_nop 0
	s_nop 0
	v_fmamk_f32 v239, v238, 0x3a800000, v158
	v_rsq_f32_e32 v21, v239
	v_mad_i64_i32 v[18:19], s[4:5], v34, s68, v[122:123]
	v_lshl_add_u64 v[18:19], v[18:19], 0, s[46:47]
	v_mul_f32_e32 v20, 0xbfb8aa3b, v21
	v_pk_mul_f32 v[12:13], v[12:13], v[20:21] op_sel_hi:[1,0]
	v_pk_mul_f32 v[10:11], v[10:11], v[20:21] op_sel_hi:[1,0]
	v_pk_mul_f32 v[8:9], v[8:9], v[20:21] op_sel_hi:[1,0]
	v_pk_mul_f32 v[6:7], v[6:7], v[20:21] op_sel_hi:[1,0]
	v_exp_f32_e32 v10, v10
	v_exp_f32_e32 v11, v11
	v_exp_f32_e32 v12, v12
	v_exp_f32_e32 v13, v13
	v_exp_f32_e32 v6, v6
	v_exp_f32_e32 v7, v7
	v_exp_f32_e32 v8, v8
	v_exp_f32_e32 v9, v9
	v_fma_f32 v10, v10, v239, v239
	v_fma_f32 v11, v11, v239, v239
	v_fma_f32 v12, v12, v239, v239
	v_fma_f32 v13, v13, v239, v239
	v_fma_f32 v20, v6, v239, v239
	v_fma_f32 v21, v7, v239, v239
	v_fma_f32 v23, v8, v239, v239
	v_fma_f32 v24, v9, v239, v239
	v_rcp_f32_e32 v6, v10
	v_rcp_f32_e32 v7, v11
	v_rcp_f32_e32 v8, v12
	v_rcp_f32_e32 v9, v13
	v_rcp_f32_e32 v10, v20
	v_rcp_f32_e32 v11, v21
	v_rcp_f32_e32 v12, v23
	v_rcp_f32_e32 v13, v24
	v_pk_mul_f32 v[8:9], v[16:17], v[8:9]
	v_pk_mul_f32 v[6:7], v[14:15], v[6:7]
	v_pk_mul_f32 v[12:13], v[4:5], v[12:13]
	v_pk_mul_f32 v[4:5], v[2:3], v[10:11]
	v_lshl_add_u64 v[18:19], v[18:19], 0, v[138:139]
	v_cvt_pk_bf16_f32 v2, v6, v7
	v_cvt_pk_bf16_f32 v3, v8, v9
	v_cvt_pk_bf16_f32 v4, v4, v5
	v_cvt_pk_bf16_f32 v5, v12, v13
	s_mov_b64 s[4:5], -1
	global_store_dwordx4 v[18:19], v[2:5], off
	s_cbranch_vccnz .LBB0_836
	s_andn2_b64 vcc, exec, s[8:9]
	s_cbranch_vccnz .LBB0_835
	s_barrier
	s_branch .LBB0_835

.Lz_post_p8b:
	s_lshl_b32 s25, s46, 8
	v_add_u32_e32 v148, s25, v150
	v_ashrrev_i32_e32 v149, 31, v148
	v_lshl_add_u64 v[160:161], v[148:149], 2, s[8:9]
	global_load_dword v149, v[160:161], off
	global_load_dword v232, v[160:161], off offset:64
	global_load_dword v233, v[160:161], off offset:128
	global_load_dword v234, v[160:161], off offset:192
	global_load_dword v235, v[160:161], off offset:512
	global_load_dword v236, v[160:161], off offset:576
	global_load_dword v237, v[160:161], off offset:640
	global_load_dword v238, v[160:161], off offset:704
	v_pk_mul_f32 v[128:129], v[120:121], v[128:129]
	v_pk_mul_f32 v[126:127], v[118:119], v[126:127]
	v_pk_mul_f32 v[124:125], v[116:117], v[124:125]
	v_pk_mul_f32 v[160:161], v[114:115], v[122:123]
	v_add_u32_e32 v162, s25, v152
	s_lshl_b32 s46, s47, 7
	v_mov_b64_e32 v[122:123], s[10:11]
	s_ashr_i32 s47, s46, 31
	v_mad_i64_i32 v[164:165], s[48:49], v148, s68, v[122:123]
	s_lshl_b64 s[46:47], s[46:47], 1
	v_lshl_add_u64 v[164:165], v[164:165], 0, s[46:47]
	v_lshl_add_u64 v[164:165], v[164:165], 0, v[138:139]
	v_pk_mul_f32 v[112:113], v[108:109], v[112:113]
	v_pk_mul_f32 v[110:111], v[106:107], v[110:111]
	v_pk_mul_f32 v[104:105], v[100:101], v[104:105]
	v_pk_mul_f32 v[102:103], v[98:99], v[102:103]
	v_pk_mul_f32 v[96:97], v[92:93], v[96:97]
	v_pk_mul_f32 v[94:95], v[90:91], v[94:95]
	v_pk_mul_f32 v[88:89], v[84:85], v[88:89]
	v_pk_mul_f32 v[86:87], v[82:83], v[86:87]
	v_pk_mul_f32 v[80:81], v[76:77], v[80:81]
	v_pk_mul_f32 v[78:79], v[74:75], v[78:79]
	v_pk_mul_f32 v[72:73], v[68:69], v[72:73]
	v_pk_mul_f32 v[70:71], v[66:67], v[70:71]
	v_pk_mul_f32 v[64:65], v[60:61], v[64:65]
	v_pk_mul_f32 v[62:63], v[58:59], v[62:63]
	v_pk_mul_f32 v[56:57], v[52:53], v[56:57]
	v_pk_mul_f32 v[54:55], v[50:51], v[54:55]
	v_pk_mul_f32 v[48:49], v[44:45], v[48:49]
	v_pk_mul_f32 v[46:47], v[42:43], v[46:47]
	v_pk_mul_f32 v[40:41], v[36:37], v[40:41]
	v_pk_mul_f32 v[38:39], v[34:35], v[38:39]
	v_pk_mul_f32 v[32:33], v[28:29], v[32:33]
	v_pk_mul_f32 v[30:31], v[26:27], v[30:31]
	v_pk_mul_f32 v[24:25], v[20:21], v[24:25]
	v_pk_mul_f32 v[22:23], v[18:19], v[22:23]
	v_pk_mul_f32 v[16:17], v[12:13], v[16:17]
	v_pk_mul_f32 v[14:15], v[10:11], v[14:15]
	v_pk_mul_f32 v[4:5], v[8:9], v[4:5]
	v_pk_mul_f32 v[2:3], v[6:7], v[2:3]
	s_and_b64 vcc, exec, s[16:17]
	s_cbranch_vccz .LBB0_1133
	s_barrier
.LBB0_1133:
	s_andn2_b64 vcc, exec, s[4:5]
	s_waitcnt vmcnt(0)
	v_fmamk_f32 v239, v149, 0x3a800000, v158
	v_rsq_f32_e32 v149, v239
	s_nop 0
	v_mul_f32_e32 v168, 0xbfb8aa3b, v149
	v_pk_mul_f32 v[120:121], v[120:121], v[168:169] op_sel_hi:[1,0]
	v_pk_mul_f32 v[118:119], v[118:119], v[168:169] op_sel_hi:[1,0]
	v_pk_mul_f32 v[116:117], v[116:117], v[168:169] op_sel_hi:[1,0]
	v_pk_mul_f32 v[114:115], v[114:115], v[168:169] op_sel_hi:[1,0]
	v_exp_f32_e32 v118, v118
	v_exp_f32_e32 v119, v119
	v_exp_f32_e32 v120, v120
	v_exp_f32_e32 v121, v121
	v_exp_f32_e32 v114, v114
	v_exp_f32_e32 v115, v115
	v_exp_f32_e32 v116, v116
	v_exp_f32_e32 v117, v117
	v_fma_f32 v118, v118, v239, v239
	v_fma_f32 v119, v119, v239, v239
	v_fma_f32 v120, v120, v239, v239
	v_fma_f32 v121, v121, v239, v239
	v_fma_f32 v149, v114, v239, v239
	v_fma_f32 v159, v115, v239, v239
	v_fma_f32 v163, v116, v239, v239
	v_fma_f32 v168, v117, v239, v239
	v_rcp_f32_e32 v114, v118
	v_rcp_f32_e32 v115, v119
	v_rcp_f32_e32 v116, v120
	v_rcp_f32_e32 v117, v121
	v_rcp_f32_e32 v118, v149
	v_rcp_f32_e32 v119, v159
	v_rcp_f32_e32 v120, v163
	v_rcp_f32_e32 v121, v168
	v_pk_mul_f32 v[116:117], v[128:129], v[116:117]
	v_pk_mul_f32 v[114:115], v[126:127], v[114:115]
	v_pk_mul_f32 v[120:121], v[124:125], v[120:121]
	v_pk_mul_f32 v[118:119], v[160:161], v[118:119]
	v_cvt_pk_bf16_f32 v114, v114, v115
	v_cvt_pk_bf16_f32 v115, v116, v117
	v_cvt_pk_bf16_f32 v116, v118, v119
	v_cvt_pk_bf16_f32 v117, v120, v121
	global_store_dwordx4 v[164:165], v[114:117], off
	v_fmamk_f32 v239, v232, 0x3a800000, v158
	v_rsq_f32_e32 v121, v239
	v_add_u32_e32 v114, s25, v153
	v_mul_f32_e32 v120, 0xbfb8aa3b, v121
	v_pk_mul_f32 v[108:109], v[108:109], v[120:121] op_sel_hi:[1,0]
	v_pk_mul_f32 v[106:107], v[106:107], v[120:121] op_sel_hi:[1,0]
	v_pk_mul_f32 v[100:101], v[100:101], v[120:121] op_sel_hi:[1,0]
	v_pk_mul_f32 v[98:99], v[98:99], v[120:121] op_sel_hi:[1,0]
	v_exp_f32_e32 v106, v106
	v_exp_f32_e32 v107, v107
	v_exp_f32_e32 v108, v108
	v_exp_f32_e32 v109, v109
	v_exp_f32_e32 v98, v98
	v_exp_f32_e32 v99, v99
	v_exp_f32_e32 v100, v100
	v_exp_f32_e32 v101, v101
	v_fma_f32 v106, v106, v239, v239
	v_fma_f32 v107, v107, v239, v239
	v_fma_f32 v108, v108, v239, v239
	v_fma_f32 v109, v109, v239, v239
	v_fma_f32 v115, v98, v239, v239
	v_fma_f32 v120, v99, v239, v239
	v_fma_f32 v121, v100, v239, v239
	v_fma_f32 v125, v101, v239, v239
	v_rcp_f32_e32 v98, v106
	v_rcp_f32_e32 v99, v107
	v_rcp_f32_e32 v100, v108
	v_rcp_f32_e32 v101, v109
	v_rcp_f32_e32 v106, v115
	v_rcp_f32_e32 v107, v120
	v_rcp_f32_e32 v108, v121
	v_rcp_f32_e32 v109, v125
	v_mad_i64_i32 v[116:117], s[48:49], v162, s68, v[122:123]
	v_lshl_add_u64 v[116:117], v[116:117], 0, s[46:47]
	v_pk_mul_f32 v[100:101], v[112:113], v[100:101]
	v_pk_mul_f32 v[98:99], v[110:111], v[98:99]
	v_pk_mul_f32 v[104:105], v[104:105], v[108:109]
	v_pk_mul_f32 v[102:103], v[102:103], v[106:107]
	v_lshl_add_u64 v[116:117], v[116:117], 0, v[138:139]
	v_cvt_pk_bf16_f32 v98, v98, v99
	v_cvt_pk_bf16_f32 v99, v100, v101
	v_cvt_pk_bf16_f32 v100, v102, v103
	v_cvt_pk_bf16_f32 v101, v104, v105
	global_store_dwordx4 v[116:117], v[98:101], off
	v_fmamk_f32 v239, v233, 0x3a800000, v158
	v_rsq_f32_e32 v105, v239
	v_add_u32_e32 v98, s25, v154
	v_mul_f32_e32 v104, 0xbfb8aa3b, v105
	v_pk_mul_f32 v[92:93], v[92:93], v[104:105] op_sel_hi:[1,0]
	v_pk_mul_f32 v[90:91], v[90:91], v[104:105] op_sel_hi:[1,0]
	v_pk_mul_f32 v[84:85], v[84:85], v[104:105] op_sel_hi:[1,0]
	v_pk_mul_f32 v[82:83], v[82:83], v[104:105] op_sel_hi:[1,0]
	v_exp_f32_e32 v90, v90
	v_exp_f32_e32 v91, v91
	v_exp_f32_e32 v92, v92
	v_exp_f32_e32 v93, v93
	v_exp_f32_e32 v82, v82
	v_exp_f32_e32 v83, v83
	v_exp_f32_e32 v84, v84
	v_exp_f32_e32 v85, v85
	v_fma_f32 v90, v90, v239, v239
	v_fma_f32 v91, v91, v239, v239
	v_fma_f32 v92, v92, v239, v239
	v_fma_f32 v93, v93, v239, v239
	v_fma_f32 v99, v82, v239, v239
	v_fma_f32 v104, v83, v239, v239
	v_fma_f32 v105, v84, v239, v239
	v_fma_f32 v107, v85, v239, v239
	v_rcp_f32_e32 v82, v90
	v_rcp_f32_e32 v83, v91
	v_rcp_f32_e32 v84, v92
	v_rcp_f32_e32 v85, v93
	v_rcp_f32_e32 v90, v99
	v_rcp_f32_e32 v91, v104
	v_rcp_f32_e32 v92, v105
	v_rcp_f32_e32 v93, v107
	v_mad_i64_i32 v[100:101], s[48:49], v114, s68, v[122:123]
	v_lshl_add_u64 v[100:101], v[100:101], 0, s[46:47]
	v_pk_mul_f32 v[84:85], v[96:97], v[84:85]
	v_pk_mul_f32 v[82:83], v[94:95], v[82:83]
	v_pk_mul_f32 v[88:89], v[88:89], v[92:93]
	v_pk_mul_f32 v[86:87], v[86:87], v[90:91]
	v_lshl_add_u64 v[100:101], v[100:101], 0, v[138:139]
	v_cvt_pk_bf16_f32 v82, v82, v83
	v_cvt_pk_bf16_f32 v83, v84, v85
	v_cvt_pk_bf16_f32 v84, v86, v87
	v_cvt_pk_bf16_f32 v85, v88, v89
	global_store_dwordx4 v[100:101], v[82:85], off
	s_nop 0
	s_nop 0
	v_add_u32_e32 v84, 0x80, v148
	v_mad_i64_i32 v[82:83], s[48:49], v98, s68, v[122:123]
	v_lshl_add_u64 v[82:83], v[82:83], 0, s[46:47]
	v_lshl_add_u64 v[82:83], v[82:83], 0, v[138:139]
	v_fmamk_f32 v239, v234, 0x3a800000, v158
	v_rsq_f32_e32 v89, v239
	s_nop 0
	v_mul_f32_e32 v88, 0xbfb8aa3b, v89
	v_pk_mul_f32 v[76:77], v[76:77], v[88:89] op_sel_hi:[1,0]
	v_pk_mul_f32 v[74:75], v[74:75], v[88:89] op_sel_hi:[1,0]
	v_pk_mul_f32 v[68:69], v[68:69], v[88:89] op_sel_hi:[1,0]
	v_pk_mul_f32 v[66:67], v[66:67], v[88:89] op_sel_hi:[1,0]
	v_exp_f32_e32 v74, v74
	v_exp_f32_e32 v75, v75
	v_exp_f32_e32 v76, v76
	v_exp_f32_e32 v77, v77
	v_exp_f32_e32 v66, v66
	v_exp_f32_e32 v67, v67
	v_exp_f32_e32 v68, v68
	v_exp_f32_e32 v69, v69
	v_fma_f32 v74, v74, v239, v239
	v_fma_f32 v75, v75, v239, v239
	v_fma_f32 v76, v76, v239, v239
	v_fma_f32 v77, v77, v239, v239
	v_fma_f32 v85, v66, v239, v239
	v_fma_f32 v88, v67, v239, v239
	v_fma_f32 v89, v68, v239, v239
	v_fma_f32 v91, v69, v239, v239
	v_rcp_f32_e32 v66, v74
	v_rcp_f32_e32 v67, v75
	v_rcp_f32_e32 v68, v76
	v_rcp_f32_e32 v69, v77
	v_rcp_f32_e32 v74, v85
	v_rcp_f32_e32 v75, v88
	v_rcp_f32_e32 v76, v89
	v_rcp_f32_e32 v77, v91
	v_pk_mul_f32 v[68:69], v[80:81], v[68:69]
	v_pk_mul_f32 v[66:67], v[78:79], v[66:67]
	v_pk_mul_f32 v[72:73], v[72:73], v[76:77]
	v_pk_mul_f32 v[70:71], v[70:71], v[74:75]
	v_cvt_pk_bf16_f32 v66, v66, v67
	v_cvt_pk_bf16_f32 v67, v68, v69
	v_cvt_pk_bf16_f32 v68, v70, v71
	v_cvt_pk_bf16_f32 v69, v72, v73
	global_store_dwordx4 v[82:83], v[66:69], off
	v_fmamk_f32 v239, v235, 0x3a800000, v158
	v_rsq_f32_e32 v73, v239
	v_add_u32_e32 v66, 0x90, v148
	v_mul_f32_e32 v72, 0xbfb8aa3b, v73
	v_pk_mul_f32 v[60:61], v[60:61], v[72:73] op_sel_hi:[1,0]
	v_pk_mul_f32 v[58:59], v[58:59], v[72:73] op_sel_hi:[1,0]
	v_pk_mul_f32 v[52:53], v[52:53], v[72:73] op_sel_hi:[1,0]
	v_pk_mul_f32 v[50:51], v[50:51], v[72:73] op_sel_hi:[1,0]
	v_exp_f32_e32 v58, v58
	v_exp_f32_e32 v59, v59
	v_exp_f32_e32 v60, v60
	v_exp_f32_e32 v61, v61
	v_exp_f32_e32 v50, v50
	v_exp_f32_e32 v51, v51
	v_exp_f32_e32 v52, v52
	v_exp_f32_e32 v53, v53
	v_fma_f32 v58, v58, v239, v239
	v_fma_f32 v59, v59, v239, v239
	v_fma_f32 v60, v60, v239, v239
	v_fma_f32 v61, v61, v239, v239
	v_fma_f32 v67, v50, v239, v239
	v_fma_f32 v72, v51, v239, v239
	v_fma_f32 v73, v52, v239, v239
	v_fma_f32 v75, v53, v239, v239
	v_rcp_f32_e32 v50, v58
	v_rcp_f32_e32 v51, v59
	v_rcp_f32_e32 v52, v60
	v_rcp_f32_e32 v53, v61
	v_rcp_f32_e32 v58, v67
	v_rcp_f32_e32 v59, v72
	v_rcp_f32_e32 v60, v73
	v_rcp_f32_e32 v61, v75
	v_mad_i64_i32 v[68:69], s[48:49], v84, s68, v[122:123]
	v_lshl_add_u64 v[68:69], v[68:69], 0, s[46:47]
	v_pk_mul_f32 v[52:53], v[64:65], v[52:53]
	v_pk_mul_f32 v[50:51], v[62:63], v[50:51]
	v_pk_mul_f32 v[56:57], v[56:57], v[60:61]
	v_pk_mul_f32 v[54:55], v[54:55], v[58:59]
	v_lshl_add_u64 v[68:69], v[68:69], 0, v[138:139]
	v_cvt_pk_bf16_f32 v50, v50, v51
	v_cvt_pk_bf16_f32 v51, v52, v53
	v_cvt_pk_bf16_f32 v52, v54, v55
	v_cvt_pk_bf16_f32 v53, v56, v57
	global_store_dwordx4 v[68:69], v[50:53], off
	v_fmamk_f32 v239, v236, 0x3a800000, v158
	v_rsq_f32_e32 v57, v239
	v_add_u32_e32 v50, 0xa0, v148
	v_mul_f32_e32 v56, 0xbfb8aa3b, v57
	v_pk_mul_f32 v[44:45], v[44:45], v[56:57] op_sel_hi:[1,0]
	v_pk_mul_f32 v[42:43], v[42:43], v[56:57] op_sel_hi:[1,0]
	v_pk_mul_f32 v[36:37], v[36:37], v[56:57] op_sel_hi:[1,0]
	v_pk_mul_f32 v[34:35], v[34:35], v[56:57] op_sel_hi:[1,0]
	v_exp_f32_e32 v42, v42
	v_exp_f32_e32 v43, v43
	v_exp_f32_e32 v44, v44
	v_exp_f32_e32 v45, v45
	v_exp_f32_e32 v34, v34
	v_exp_f32_e32 v35, v35
	v_exp_f32_e32 v36, v36
	v_exp_f32_e32 v37, v37
	v_fma_f32 v42, v42, v239, v239
	v_fma_f32 v43, v43, v239, v239
	v_fma_f32 v44, v44, v239, v239
	v_fma_f32 v45, v45, v239, v239
	v_fma_f32 v51, v34, v239, v239
	v_fma_f32 v56, v35, v239, v239
	v_fma_f32 v57, v36, v239, v239
	v_fma_f32 v59, v37, v239, v239
	v_rcp_f32_e32 v34, v42
	v_rcp_f32_e32 v35, v43
	v_rcp_f32_e32 v36, v44
	v_rcp_f32_e32 v37, v45
	v_rcp_f32_e32 v42, v51
	v_rcp_f32_e32 v43, v56
	v_rcp_f32_e32 v44, v57
	v_rcp_f32_e32 v45, v59
	v_mad_i64_i32 v[52:53], s[48:49], v66, s68, v[122:123]
	v_lshl_add_u64 v[52:53], v[52:53], 0, s[46:47]
	v_pk_mul_f32 v[36:37], v[48:49], v[36:37]
	v_pk_mul_f32 v[34:35], v[46:47], v[34:35]
	v_pk_mul_f32 v[40:41], v[40:41], v[44:45]
	v_pk_mul_f32 v[38:39], v[38:39], v[42:43]
	v_lshl_add_u64 v[52:53], v[52:53], 0, v[138:139]
	v_cvt_pk_bf16_f32 v34, v34, v35
	v_cvt_pk_bf16_f32 v35, v36, v37
	v_cvt_pk_bf16_f32 v36, v38, v39
	v_cvt_pk_bf16_f32 v37, v40, v41
	global_store_dwordx4 v[52:53], v[34:37], off
	v_fmamk_f32 v239, v237, 0x3a800000, v158
	v_rsq_f32_e32 v41, v239
	v_add_u32_e32 v34, 0xb0, v148
	v_mul_f32_e32 v40, 0xbfb8aa3b, v41
	v_pk_mul_f32 v[28:29], v[28:29], v[40:41] op_sel_hi:[1,0]
	v_pk_mul_f32 v[26:27], v[26:27], v[40:41] op_sel_hi:[1,0]
	v_pk_mul_f32 v[20:21], v[20:21], v[40:41] op_sel_hi:[1,0]
	v_pk_mul_f32 v[18:19], v[18:19], v[40:41] op_sel_hi:[1,0]
	v_exp_f32_e32 v26, v26
	v_exp_f32_e32 v27, v27
	v_exp_f32_e32 v28, v28
	v_exp_f32_e32 v29, v29
	v_exp_f32_e32 v18, v18
	v_exp_f32_e32 v19, v19
	v_exp_f32_e32 v20, v20
	v_exp_f32_e32 v21, v21
	v_fma_f32 v26, v26, v239, v239
	v_fma_f32 v27, v27, v239, v239
	v_fma_f32 v28, v28, v239, v239
	v_fma_f32 v29, v29, v239, v239
	v_fma_f32 v35, v18, v239, v239
	v_fma_f32 v40, v19, v239, v239
	v_fma_f32 v41, v20, v239, v239
	v_fma_f32 v43, v21, v239, v239
	v_rcp_f32_e32 v18, v26
	v_rcp_f32_e32 v19, v27
	v_rcp_f32_e32 v20, v28
	v_rcp_f32_e32 v21, v29
	v_rcp_f32_e32 v26, v35
	v_rcp_f32_e32 v27, v40
	v_rcp_f32_e32 v28, v41
	v_rcp_f32_e32 v29, v43
	v_mad_i64_i32 v[36:37], s[48:49], v50, s68, v[122:123]
	v_lshl_add_u64 v[36:37], v[36:37], 0, s[46:47]
	v_pk_mul_f32 v[20:21], v[32:33], v[20:21]
	v_pk_mul_f32 v[18:19], v[30:31], v[18:19]
	v_pk_mul_f32 v[24:25], v[24:25], v[28:29]
	v_pk_mul_f32 v[22:23], v[22:23], v[26:27]
	v_lshl_add_u64 v[36:37], v[36:37], 0, v[138:139]
	v_cvt_pk_bf16_f32 v18, v18, v19
	v_cvt_pk_bf16_f32 v19, v20, v21
	v_cvt_pk_bf16_f32 v20, v22, v23
	v_cvt_pk_bf16_f32 v21, v24, v25
	global_store_dwordx4 v[36:37], v[18:21], off
	s_nop 0
	s_nop 0
	v_fmamk_f32 v239, v238, 0x3a800000, v158
	v_rsq_f32_e32 v21, v239
	v_mad_i64_i32 v[18:19], s[4:5], v34, s68, v[122:123]
	v_lshl_add_u64 v[18:19], v[18:19], 0, s[46:47]
	v_mul_f32_e32 v20, 0xbfb8aa3b, v21
	v_pk_mul_f32 v[12:13], v[12:13], v[20:21] op_sel_hi:[1,0]
	v_pk_mul_f32 v[10:11], v[10:11], v[20:21] op_sel_hi:[1,0]
	v_pk_mul_f32 v[8:9], v[8:9], v[20:21] op_sel_hi:[1,0]
	v_pk_mul_f32 v[6:7], v[6:7], v[20:21] op_sel_hi:[1,0]
	v_exp_f32_e32 v10, v10
	v_exp_f32_e32 v11, v11
	v_exp_f32_e32 v12, v12
	v_exp_f32_e32 v13, v13
	v_exp_f32_e32 v6, v6
	v_exp_f32_e32 v7, v7
	v_exp_f32_e32 v8, v8
	v_exp_f32_e32 v9, v9
	v_fma_f32 v10, v10, v239, v239
	v_fma_f32 v11, v11, v239, v239
	v_fma_f32 v12, v12, v239, v239
	v_fma_f32 v13, v13, v239, v239
	v_fma_f32 v20, v6, v239, v239
	v_fma_f32 v21, v7, v239, v239
	v_fma_f32 v23, v8, v239, v239
	v_fma_f32 v24, v9, v239, v239
	v_rcp_f32_e32 v6, v10
	v_rcp_f32_e32 v7, v11
	v_rcp_f32_e32 v8, v12
	v_rcp_f32_e32 v9, v13
	v_rcp_f32_e32 v10, v20
	v_rcp_f32_e32 v11, v21
	v_rcp_f32_e32 v12, v23
	v_rcp_f32_e32 v13, v24
	v_pk_mul_f32 v[8:9], v[16:17], v[8:9]
	v_pk_mul_f32 v[6:7], v[14:15], v[6:7]
	v_pk_mul_f32 v[12:13], v[4:5], v[12:13]
	v_pk_mul_f32 v[4:5], v[2:3], v[10:11]
	v_lshl_add_u64 v[18:19], v[18:19], 0, v[138:139]
	v_cvt_pk_bf16_f32 v2, v6, v7
	v_cvt_pk_bf16_f32 v3, v8, v9
	v_cvt_pk_bf16_f32 v4, v4, v5
	v_cvt_pk_bf16_f32 v5, v12, v13
	s_mov_b64 s[4:5], -1
	global_store_dwordx4 v[18:19], v[2:5], off
	s_cbranch_vccnz .LBB0_1126
	s_andn2_b64 vcc, exec, s[6:7]
	s_cbranch_vccnz .LBB0_1125
	s_barrier
	s_branch .LBB0_1125

.LBB0_1223:
	s_ashr_i32 s46, s48, 3
	s_add_i32 s46, s50, s46
	s_ashr_i32 s47, s46, 31
	s_lshr_b32 s47, s47, 26
	s_add_i32 s47, s46, s47
	s_ashr_i32 s48, s47, 6
	s_lshl_b32 s48, s48, 3
	s_andn2_b32 s47, s47, 63
	s_sub_i32 s47, s46, s47
	s_lshr_b32 s46, s47, 3
	s_and_b32 s47, s47, 7
	s_add_i32 s48, s48, s47

.LBB0_1354:
	s_add_i32 s65, s65, 1
	s_mul_i32 s6, s65, s68
	s_mul_hi_u32 s7, s65, s69
	s_add_i32 s7, s7, s6
	s_mul_i32 s6, s65, s69
	s_add_u32 s46, s6, s2
	s_addc_u32 s47, s7, s70
	v_cmp_gt_i64_e32 vcc, s[46:47], v[146:147]
	v_cmp_lt_i64_e64 s[6:7], s[46:47], v[144:145]
	s_cbranch_vccnz .LBB0_1356
	s_ashr_i32 s42, s46, 31
	s_lshr_b32 s42, s42, 29
	s_add_i32 s42, s46, s42
	s_ashr_i32 s43, s42, 3
	s_and_b32 s42, s42, -8
	s_sub_i32 s42, s46, s42
	s_cmp_lt_i32 s42, 0
	s_cselect_b32 s44, 49, 48
	s_mul_i32 s42, s42, s44
	s_add_i32 s42, s42, s43
	s_mul_hi_i32 s43, s42, 0x2aaaaaab
	s_lshr_b32 s44, s43, 31
	s_ashr_i32 s43, s43, 2
	s_add_i32 s43, s43, s44
	s_lshl_b32 s44, s43, 3
	s_mul_i32 s43, s43, 24
	s_sub_i32 s43, s42, s43
	s_lshr_b32 s42, s43, 3
	s_and_b32 s43, s43, 7
	s_add_i32 s44, s44, s43

.LBB0_1479:
	s_add_i32 s74, s74, 1
	s_mul_i32 s4, s74, s64
	s_mul_hi_u32 s5, s74, s65
	s_add_i32 s5, s5, s4
	s_mul_i32 s4, s74, s65
	s_add_u32 s4, s4, s2
	s_addc_u32 s5, s5, s66
	v_cmp_gt_i64_e32 vcc, s[4:5], v[150:151]
	v_cmp_lt_i64_e64 s[6:7], s[4:5], v[148:149]
	s_cbranch_vccnz .LBB0_1481
	s_ashr_i32 s5, s4, 31
	s_lshr_b32 s5, s5, 29
	s_add_i32 s5, s4, s5
	s_ashr_i32 s10, s5, 3
	s_and_b32 s5, s5, -8
	s_sub_i32 s4, s4, s5
	s_cmp_lt_i32 s4, 0
	s_cselect_b32 s5, s67, 0x60
	s_mul_i32 s4, s4, s5
	s_add_i32 s4, s4, s10
	s_mul_hi_i32 s5, s4, 0x2aaaaaab
	s_lshr_b32 s10, s5, 31
	s_ashr_i32 s5, s5, 3
	s_add_i32 s5, s5, s10
	s_lshl_b32 s10, s5, 3
	s_mul_i32 s5, s5, 48
	s_sub_i32 s4, s4, s5
	s_lshr_b32 s75, s4, 3
	s_and_b32 s4, s4, 7
	s_add_i32 s76, s10, s4
